# grid barrier: non-leader workgroups spin on the top-level generation word directly (one relay hop fewer)
# speedup vs baseline: 1.0247x; 1.0070x over previous
.LBB0_165:
	s_or_b64 exec, exec, s[10:11]
	v_cvt_f32_u32_e32 v4, v2
	s_waitcnt vmcnt(0)
	v_readfirstlane_b32 s3, v3
	v_sub_u32_e32 v3, 0, v2
	v_rcp_iflag_f32_e32 v4, v4
	v_add_u32_e32 v5, s3, v1
	v_mul_f32_e32 v4, 0x4f7ffffe, v4
	v_cvt_u32_f32_e32 v4, v4
	v_mul_lo_u32 v1, v3, v4
	v_mul_hi_u32 v1, v4, v1
	v_add_u32_e32 v1, v4, v1
	v_mul_hi_u32 v1, v5, v1
	v_mul_lo_u32 v3, v1, v2
	v_sub_u32_e32 v3, v5, v3
	v_add_u32_e32 v4, 1, v1
	v_sub_u32_e32 v6, v3, v2
	v_cmp_ge_u32_e32 vcc, v3, v2
	s_nop 1
	v_cndmask_b32_e32 v1, v1, v4, vcc
	v_cndmask_b32_e32 v3, v3, v6, vcc
	v_add_u32_e32 v4, 1, v1
	v_cmp_ge_u32_e32 vcc, v3, v2
	v_add_u32_e32 v3, 1, v5
	s_nop 0
	v_cndmask_b32_e32 v1, v1, v4, vcc
	v_mul_lo_u32 v4, v2, v1
	v_add_u32_e32 v2, v4, v2
	v_cmp_ne_u32_e32 vcc, v3, v2
	s_and_saveexec_b64 s[8:9], vcc
	s_xor_b64 s[8:9], exec, s[8:9]
	s_cbranch_execz .LBB0_179
	s_waitcnt lgkmcnt(0)
	v_mov_b32_e32 v0, 0x3100
	buffer_inv sc1
	global_load_dword v0, v0, s[54:55] offset:1024 sc1
	s_add_u32 s12, s54, 0x3500
	s_addc_u32 s13, s55, 0
	s_waitcnt vmcnt(0)
	v_cmp_eq_u32_e32 vcc, v0, v1
	s_and_saveexec_b64 s[10:11], vcc
	s_cbranch_execz .LBB0_178
	s_mov_b32 s3, 1
	s_mov_b64 s[14:15], 0
	v_mov_b32_e32 v0, 0
	s_branch .LBB0_169

.LBB0_438:
	s_or_b64 exec, exec, s[8:9]
	v_cvt_f32_u32_e32 v4, v2
	s_waitcnt vmcnt(0)
	v_readfirstlane_b32 s3, v3
	v_sub_u32_e32 v3, 0, v2
	v_rcp_iflag_f32_e32 v4, v4
	v_add_u32_e32 v5, s3, v1
	v_mul_f32_e32 v4, 0x4f7ffffe, v4
	v_cvt_u32_f32_e32 v4, v4
	v_mul_lo_u32 v1, v3, v4
	v_mul_hi_u32 v1, v4, v1
	v_add_u32_e32 v1, v4, v1
	v_mul_hi_u32 v1, v5, v1
	v_mul_lo_u32 v3, v1, v2
	v_sub_u32_e32 v3, v5, v3
	v_add_u32_e32 v4, 1, v1
	v_cmp_ge_u32_e32 vcc, v3, v2
	s_nop 1
	v_cndmask_b32_e32 v1, v1, v4, vcc
	v_sub_u32_e32 v4, v3, v2
	v_cndmask_b32_e32 v3, v3, v4, vcc
	v_add_u32_e32 v4, 1, v1
	v_cmp_ge_u32_e32 vcc, v3, v2
	v_add_u32_e32 v3, 1, v5
	s_nop 0
	v_cndmask_b32_e32 v1, v1, v4, vcc
	v_mul_lo_u32 v4, v2, v1
	v_add_u32_e32 v2, v4, v2
	v_cmp_ne_u32_e32 vcc, v3, v2
	s_and_saveexec_b64 s[6:7], vcc
	s_xor_b64 s[6:7], exec, s[6:7]
	s_cbranch_execz .LBB0_452
	s_waitcnt lgkmcnt(0)
	v_mov_b32_e32 v0, 0x3100
	buffer_inv sc1
	global_load_dword v0, v0, s[54:55] offset:1024 sc1
	s_add_u32 s10, s54, 0x3500
	s_addc_u32 s11, s55, 0
	s_waitcnt vmcnt(0)
	v_cmp_eq_u32_e32 vcc, v0, v1
	s_and_saveexec_b64 s[8:9], vcc
	s_cbranch_execz .LBB0_451
	s_mov_b32 s3, 1
	s_mov_b64 s[12:13], 0
	v_mov_b32_e32 v0, 0
	s_branch .LBB0_442

.LBB0_818:
	s_or_b64 exec, exec, s[8:9]
	v_cvt_f32_u32_e32 v144, v142
	s_waitcnt vmcnt(0)
	v_readfirstlane_b32 s3, v143
	v_sub_u32_e32 v143, 0, v142
	v_rcp_iflag_f32_e32 v144, v144
	v_add_u32_e32 v145, s3, v141
	v_mul_f32_e32 v144, 0x4f7ffffe, v144
	v_cvt_u32_f32_e32 v144, v144
	v_mul_lo_u32 v141, v143, v144
	v_mul_hi_u32 v141, v144, v141
	v_add_u32_e32 v141, v144, v141
	v_mul_hi_u32 v141, v145, v141
	v_mul_lo_u32 v143, v141, v142
	v_sub_u32_e32 v143, v145, v143
	v_add_u32_e32 v144, 1, v141
	v_cmp_ge_u32_e32 vcc, v143, v142
	s_nop 1
	v_cndmask_b32_e32 v141, v141, v144, vcc
	v_sub_u32_e32 v144, v143, v142
	v_cndmask_b32_e32 v143, v143, v144, vcc
	v_add_u32_e32 v144, 1, v141
	v_cmp_ge_u32_e32 vcc, v143, v142
	v_add_u32_e32 v143, 1, v145
	s_nop 0
	v_cndmask_b32_e32 v141, v141, v144, vcc
	v_mul_lo_u32 v144, v142, v141
	v_add_u32_e32 v142, v144, v142
	v_cmp_ne_u32_e32 vcc, v143, v142
	s_and_saveexec_b64 s[6:7], vcc
	s_xor_b64 s[6:7], exec, s[6:7]
	s_cbranch_execz .LBB0_832
	s_waitcnt lgkmcnt(0)
	v_mov_b32_e32 v140, 0x3100
	buffer_inv sc1
	global_load_dword v140, v140, s[54:55] offset:1024 sc1
	s_add_u32 s12, s54, 0x3500
	s_addc_u32 s13, s55, 0
	s_waitcnt vmcnt(0)
	v_cmp_eq_u32_e32 vcc, v140, v141
	s_and_saveexec_b64 s[8:9], vcc
	s_cbranch_execz .LBB0_831
	s_mov_b32 s3, 1
	s_mov_b64 s[14:15], 0
	v_mov_b32_e32 v140, 0
	s_branch .LBB0_822

.LBB0_881:
	s_or_b64 exec, exec, s[12:13]
	v_cvt_f32_u32_e32 v4, v2
	s_waitcnt vmcnt(0)
	v_readfirstlane_b32 s3, v3
	v_sub_u32_e32 v3, 0, v2
	v_rcp_iflag_f32_e32 v4, v4
	v_add_u32_e32 v5, s3, v1
	v_mul_f32_e32 v4, 0x4f7ffffe, v4
	v_cvt_u32_f32_e32 v4, v4
	v_mul_lo_u32 v1, v3, v4
	v_mul_hi_u32 v1, v4, v1
	v_add_u32_e32 v1, v4, v1
	v_mul_hi_u32 v1, v5, v1
	v_mul_lo_u32 v3, v1, v2
	v_sub_u32_e32 v3, v5, v3
	v_add_u32_e32 v4, 1, v1
	v_cmp_ge_u32_e32 vcc, v3, v2
	s_nop 1
	v_cndmask_b32_e32 v1, v1, v4, vcc
	v_sub_u32_e32 v4, v3, v2
	v_cndmask_b32_e32 v3, v3, v4, vcc
	v_add_u32_e32 v4, 1, v1
	v_cmp_ge_u32_e32 vcc, v3, v2
	v_add_u32_e32 v3, 1, v5
	s_nop 0
	v_cndmask_b32_e32 v1, v1, v4, vcc
	v_mul_lo_u32 v4, v2, v1
	v_add_u32_e32 v2, v4, v2
	v_cmp_ne_u32_e32 vcc, v3, v2
	s_and_saveexec_b64 s[6:7], vcc
	s_xor_b64 s[6:7], exec, s[6:7]
	s_cbranch_execz .LBB0_895
	s_waitcnt lgkmcnt(0)
	v_mov_b32_e32 v0, 0x3100
	buffer_inv sc1
	global_load_dword v0, v0, s[54:55] offset:1024 sc1
	s_add_u32 s14, s54, 0x3500
	s_addc_u32 s15, s55, 0
	s_waitcnt vmcnt(0)
	v_cmp_eq_u32_e32 vcc, v0, v1
	s_and_saveexec_b64 s[12:13], vcc
	s_cbranch_execz .LBB0_894
	s_mov_b32 s3, 1
	s_mov_b64 s[16:17], 0
	v_mov_b32_e32 v0, 0
	s_branch .LBB0_885

.LBB0_948:
	s_or_b64 exec, exec, s[14:15]
	v_cvt_f32_u32_e32 v4, v2
	s_waitcnt vmcnt(0)
	v_readfirstlane_b32 s3, v3
	v_sub_u32_e32 v3, 0, v2
	v_rcp_iflag_f32_e32 v4, v4
	v_add_u32_e32 v5, s3, v1
	v_mul_f32_e32 v4, 0x4f7ffffe, v4
	v_cvt_u32_f32_e32 v4, v4
	v_mul_lo_u32 v1, v3, v4
	v_mul_hi_u32 v1, v4, v1
	v_add_u32_e32 v1, v4, v1
	v_mul_hi_u32 v1, v5, v1
	v_mul_lo_u32 v3, v1, v2
	v_sub_u32_e32 v3, v5, v3
	v_add_u32_e32 v4, 1, v1
	v_cmp_ge_u32_e32 vcc, v3, v2
	s_nop 1
	v_cndmask_b32_e32 v1, v1, v4, vcc
	v_sub_u32_e32 v4, v3, v2
	v_cndmask_b32_e32 v3, v3, v4, vcc
	v_add_u32_e32 v4, 1, v1
	v_cmp_ge_u32_e32 vcc, v3, v2
	v_add_u32_e32 v3, 1, v5
	s_nop 0
	v_cndmask_b32_e32 v1, v1, v4, vcc
	v_mul_lo_u32 v4, v2, v1
	v_add_u32_e32 v2, v4, v2
	v_cmp_ne_u32_e32 vcc, v3, v2
	s_and_saveexec_b64 s[12:13], vcc
	s_xor_b64 s[12:13], exec, s[12:13]
	s_cbranch_execz .LBB0_962
	s_waitcnt lgkmcnt(0)
	v_mov_b32_e32 v0, 0x3100
	buffer_inv sc1
	global_load_dword v0, v0, s[54:55] offset:1024 sc1
	s_add_u32 s16, s54, 0x3500
	s_addc_u32 s17, s55, 0
	s_waitcnt vmcnt(0)
	v_cmp_eq_u32_e32 vcc, v0, v1
	s_and_saveexec_b64 s[14:15], vcc
	s_cbranch_execz .LBB0_961
	s_mov_b32 s3, 1
	s_mov_b64 s[18:19], 0
	v_mov_b32_e32 v0, 0
	s_branch .LBB0_952

.LBB0_1125:
	s_or_b64 exec, exec, s[12:13]
	v_cvt_f32_u32_e32 v4, v2
	s_waitcnt vmcnt(0)
	v_readfirstlane_b32 s3, v3
	v_sub_u32_e32 v3, 0, v2
	v_rcp_iflag_f32_e32 v4, v4
	v_add_u32_e32 v5, s3, v1
	v_mul_f32_e32 v4, 0x4f7ffffe, v4
	v_cvt_u32_f32_e32 v4, v4
	v_mul_lo_u32 v1, v3, v4
	v_mul_hi_u32 v1, v4, v1
	v_add_u32_e32 v1, v4, v1
	v_mul_hi_u32 v1, v5, v1
	v_mul_lo_u32 v3, v1, v2
	v_sub_u32_e32 v3, v5, v3
	v_add_u32_e32 v4, 1, v1
	v_cmp_ge_u32_e32 vcc, v3, v2
	s_nop 1
	v_cndmask_b32_e32 v1, v1, v4, vcc
	v_sub_u32_e32 v4, v3, v2
	v_cndmask_b32_e32 v3, v3, v4, vcc
	v_add_u32_e32 v4, 1, v1
	v_cmp_ge_u32_e32 vcc, v3, v2
	v_add_u32_e32 v3, 1, v5
	s_nop 0
	v_cndmask_b32_e32 v1, v1, v4, vcc
	v_mul_lo_u32 v4, v2, v1
	v_add_u32_e32 v2, v4, v2
	v_cmp_ne_u32_e32 vcc, v3, v2
	s_and_saveexec_b64 s[10:11], vcc
	s_xor_b64 s[10:11], exec, s[10:11]
	s_cbranch_execz .LBB0_1139
	s_waitcnt lgkmcnt(0)
	v_mov_b32_e32 v0, 0x3100
	buffer_inv sc1
	global_load_dword v0, v0, s[54:55] offset:1024 sc1
	s_add_u32 s14, s54, 0x3500
	s_addc_u32 s15, s55, 0
	s_waitcnt vmcnt(0)
	v_cmp_eq_u32_e32 vcc, v0, v1
	s_and_saveexec_b64 s[12:13], vcc
	s_cbranch_execz .LBB0_1138
	s_mov_b32 s3, 1
	s_mov_b64 s[16:17], 0
	v_mov_b32_e32 v0, 0
	s_branch .LBB0_1129

.LBB0_1209:
	s_or_b64 exec, exec, s[12:13]
	v_cvt_f32_u32_e32 v144, v142
	s_waitcnt vmcnt(0)
	v_readfirstlane_b32 s3, v143
	v_sub_u32_e32 v143, 0, v142
	v_rcp_iflag_f32_e32 v144, v144
	v_add_u32_e32 v145, s3, v141
	v_mul_f32_e32 v144, 0x4f7ffffe, v144
	v_cvt_u32_f32_e32 v144, v144
	v_mul_lo_u32 v141, v143, v144
	v_mul_hi_u32 v141, v144, v141
	v_add_u32_e32 v141, v144, v141
	v_mul_hi_u32 v141, v145, v141
	v_mul_lo_u32 v143, v141, v142
	v_sub_u32_e32 v143, v145, v143
	v_add_u32_e32 v144, 1, v141
	v_cmp_ge_u32_e32 vcc, v143, v142
	s_nop 1
	v_cndmask_b32_e32 v141, v141, v144, vcc
	v_sub_u32_e32 v144, v143, v142
	v_cndmask_b32_e32 v143, v143, v144, vcc
	v_add_u32_e32 v144, 1, v141
	v_cmp_ge_u32_e32 vcc, v143, v142
	v_add_u32_e32 v143, 1, v145
	s_nop 0
	v_cndmask_b32_e32 v141, v141, v144, vcc
	v_mul_lo_u32 v144, v142, v141
	v_add_u32_e32 v142, v144, v142
	v_cmp_ne_u32_e32 vcc, v143, v142
	s_and_saveexec_b64 s[10:11], vcc
	s_xor_b64 s[10:11], exec, s[10:11]
	s_cbranch_execz .LBB0_1223
	s_waitcnt lgkmcnt(0)
	v_mov_b32_e32 v140, 0x3100
	buffer_inv sc1
	global_load_dword v140, v140, s[54:55] offset:1024 sc1
	s_add_u32 s14, s54, 0x3500
	s_addc_u32 s15, s55, 0
	s_waitcnt vmcnt(0)
	v_cmp_eq_u32_e32 vcc, v140, v141
	s_and_saveexec_b64 s[12:13], vcc
	s_cbranch_execz .LBB0_1222
	s_mov_b32 s3, 1
	s_mov_b64 s[16:17], 0
	v_mov_b32_e32 v140, 0
	s_branch .LBB0_1213

.LBB0_1434:
	s_or_b64 exec, exec, s[10:11]
	v_cvt_f32_u32_e32 v144, v142
	s_waitcnt vmcnt(0)
	v_readfirstlane_b32 s3, v143
	v_sub_u32_e32 v143, 0, v142
	v_rcp_iflag_f32_e32 v144, v144
	v_add_u32_e32 v145, s3, v141
	v_mul_f32_e32 v144, 0x4f7ffffe, v144
	v_cvt_u32_f32_e32 v144, v144
	v_mul_lo_u32 v141, v143, v144
	v_mul_hi_u32 v141, v144, v141
	v_add_u32_e32 v141, v144, v141
	v_mul_hi_u32 v141, v145, v141
	v_mul_lo_u32 v143, v141, v142
	v_sub_u32_e32 v143, v145, v143
	v_add_u32_e32 v144, 1, v141
	v_cmp_ge_u32_e32 vcc, v143, v142
	s_nop 1
	v_cndmask_b32_e32 v141, v141, v144, vcc
	v_sub_u32_e32 v144, v143, v142
	v_cndmask_b32_e32 v143, v143, v144, vcc
	v_add_u32_e32 v144, 1, v141
	v_cmp_ge_u32_e32 vcc, v143, v142
	v_add_u32_e32 v143, 1, v145
	s_nop 0
	v_cndmask_b32_e32 v141, v141, v144, vcc
	v_mul_lo_u32 v144, v142, v141
	v_add_u32_e32 v142, v144, v142
	v_cmp_ne_u32_e32 vcc, v143, v142
	s_and_saveexec_b64 s[8:9], vcc
	s_xor_b64 s[8:9], exec, s[8:9]
	s_cbranch_execz .LBB0_1448
	s_waitcnt lgkmcnt(0)
	v_mov_b32_e32 v140, 0x3100
	buffer_inv sc1
	global_load_dword v140, v140, s[54:55] offset:1024 sc1
	s_add_u32 s12, s54, 0x3500
	s_addc_u32 s13, s55, 0
	s_waitcnt vmcnt(0)
	v_cmp_eq_u32_e32 vcc, v140, v141
	s_and_saveexec_b64 s[10:11], vcc
	s_cbranch_execz .LBB0_1447
	s_mov_b32 s3, 1
	s_mov_b64 s[14:15], 0
	v_mov_b32_e32 v140, 0
	s_branch .LBB0_1438
